# P8: row statistics requested in the last K-trip and passed to the epilogue through an LDS table
# speedup vs baseline: 1.0016x; 1.0016x over previous
.LBB0_971:
	ds_read_b128 v[156:159], v151
	ds_read_b128 v[160:163], v151 offset:1024
	ds_read_b128 v[164:167], v151 offset:2048
	ds_read_b128 v[168:171], v151 offset:3072
	ds_read_b128 v[172:175], v153
	ds_read_b128 v[176:179], v153 offset:1024
	ds_read_b128 v[180:183], v153 offset:2048
	ds_read_b128 v[184:187], v153 offset:3072
	s_add_u32 s6, s64, s12
	s_addc_u32 s7, s65, 0
	s_add_u32 s68, s66, s12
	s_addc_u32 s69, s67, 0
	s_cmp_eq_u32 s12, s0
	s_cselect_b32 s9, s37, s7
	s_cselect_b32 s8, s61, s6
	s_cselect_b32 s7, s35, s69
	s_cselect_b32 s6, s62, s68
	s_add_i32 s69, s46, 0xc000
	v_lshl_add_u64 v[138:139], v[142:143], 0, s[12:13]
	s_mov_b32 m0, s69
	s_add_i32 s68, s46, 0xe000
	ds_read_b128 v[188:191], v155
	ds_read_b128 v[192:195], v155 offset:1024
	ds_read_b128 v[196:199], v155 offset:2048
	ds_read_b128 v[200:203], v155 offset:3072
	ds_read_b128 v[204:207], v155 offset:4096
	ds_read_b128 v[208:211], v155 offset:5120
	ds_read_b128 v[212:215], v155 offset:6144
	ds_read_b128 v[216:219], v155 offset:7168
	global_load_lds_dwordx4 v[138:139], off
	v_lshl_add_u64 v[138:139], v[144:145], 0, s[12:13]
	s_mov_b32 m0, s68
	s_nop 0
	global_load_lds_dwordx4 v[138:139], off
	s_waitcnt vmcnt(8)
	s_waitcnt lgkmcnt(0)
	s_barrier
	s_setprio 1
	s_waitcnt lgkmcnt(0)
	v_mfma_f32_16x16x32_bf16 v[126:129], v[156:159], v[188:191], v[126:129]
	v_mfma_f32_16x16x32_bf16 v[122:125], v[164:167], v[188:191], v[122:125]
	v_mfma_f32_16x16x32_bf16 v[110:113], v[156:159], v[196:199], v[110:113]
	v_mfma_f32_16x16x32_bf16 v[106:109], v[164:167], v[196:199], v[106:109]
	v_mfma_f32_16x16x32_bf16 v[94:97], v[156:159], v[204:207], v[94:97]
	v_mfma_f32_16x16x32_bf16 v[90:93], v[164:167], v[204:207], v[90:93]
	v_mfma_f32_16x16x32_bf16 v[78:81], v[156:159], v[212:215], v[78:81]
	v_mfma_f32_16x16x32_bf16 v[74:77], v[164:167], v[212:215], v[74:77]
	v_mfma_f32_16x16x32_bf16 v[126:129], v[160:163], v[192:195], v[126:129]
	v_mfma_f32_16x16x32_bf16 v[122:125], v[168:171], v[192:195], v[122:125]
	v_mfma_f32_16x16x32_bf16 v[110:113], v[160:163], v[200:203], v[110:113]
	v_mfma_f32_16x16x32_bf16 v[106:109], v[168:171], v[200:203], v[106:109]
	v_mfma_f32_16x16x32_bf16 v[94:97], v[160:163], v[208:211], v[94:97]
	v_mfma_f32_16x16x32_bf16 v[90:93], v[168:171], v[208:211], v[90:93]
	v_mfma_f32_16x16x32_bf16 v[78:81], v[160:163], v[216:219], v[78:81]
	v_mfma_f32_16x16x32_bf16 v[74:77], v[168:171], v[216:219], v[74:77]
	s_setprio 0
	s_setprio 1
	v_mfma_f32_16x16x32_bf16 v[118:121], v[172:175], v[188:191], v[118:121]
	v_mfma_f32_16x16x32_bf16 v[114:117], v[180:183], v[188:191], v[114:117]
	v_mfma_f32_16x16x32_bf16 v[102:105], v[172:175], v[196:199], v[102:105]
	v_mfma_f32_16x16x32_bf16 v[98:101], v[180:183], v[196:199], v[98:101]
	v_mfma_f32_16x16x32_bf16 v[86:89], v[172:175], v[204:207], v[86:89]
	v_mfma_f32_16x16x32_bf16 v[82:85], v[180:183], v[204:207], v[82:85]
	v_mfma_f32_16x16x32_bf16 v[70:73], v[172:175], v[212:215], v[70:73]
	v_mfma_f32_16x16x32_bf16 v[66:69], v[180:183], v[212:215], v[66:69]
	v_mfma_f32_16x16x32_bf16 v[118:121], v[176:179], v[192:195], v[118:121]
	v_mfma_f32_16x16x32_bf16 v[114:117], v[184:187], v[192:195], v[114:117]
	v_mfma_f32_16x16x32_bf16 v[102:105], v[176:179], v[200:203], v[102:105]
	v_mfma_f32_16x16x32_bf16 v[98:101], v[184:187], v[200:203], v[98:101]
	v_mfma_f32_16x16x32_bf16 v[86:89], v[176:179], v[208:211], v[86:89]
	v_mfma_f32_16x16x32_bf16 v[82:85], v[184:187], v[208:211], v[82:85]
	v_mfma_f32_16x16x32_bf16 v[70:73], v[176:179], v[216:219], v[70:73]
	v_mfma_f32_16x16x32_bf16 v[66:69], v[184:187], v[216:219], v[66:69]
	s_setprio 0
	s_barrier
	s_cmp_lg_u32 s12, s0
	s_cbranch_scc1 .Lmy_p8_noload
	s_lshl_b32 s98, s4, 14
	v_lshl_add_u32 v252, v0, 5, s98
	global_load_dwordx4 v[228:231], v252, s[16:17]
	global_load_dwordx4 v[232:235], v252, s[16:17] offset:16
.Lmy_p8_noload:
	s_add_i32 s70, s57, s45
	v_lshl_add_u64 v[138:139], s[6:7], 0, v[132:133]
	s_mov_b32 m0, s70
	ds_read_b128 v[188:191], v155 offset:16384
	ds_read_b128 v[192:195], v155 offset:17408
	ds_read_b128 v[196:199], v155 offset:18432
	ds_read_b128 v[200:203], v155 offset:19456
	ds_read_b128 v[204:207], v155 offset:20480
	ds_read_b128 v[208:211], v155 offset:21504
	ds_read_b128 v[212:215], v155 offset:22528
	ds_read_b128 v[216:219], v155 offset:23552
	global_load_lds_dwordx4 v[138:139], off
	s_add_i32 m0, s70, 0x2000
	s_add_u32 s70, s6, 0x10000
	v_lshl_add_u64 v[220:221], s[6:7], 0, v[136:137]
	s_addc_u32 s71, s7, 0
	s_add_i32 s72, s58, s45
	global_load_lds_dwordx4 v[220:221], off
	v_lshl_add_u64 v[222:223], s[70:71], 0, v[132:133]
	s_mov_b32 m0, s72
	v_lshl_add_u64 v[224:225], s[8:9], 0, v[134:135]
	global_load_lds_dwordx4 v[222:223], off
	v_lshl_add_u64 v[222:223], s[70:71], 0, v[136:137]
	s_add_i32 m0, s72, 0x2000
	s_nop 0
	global_load_lds_dwordx4 v[222:223], off
	v_lshl_add_u64 v[222:223], s[8:9], 0, v[130:131]
	s_mov_b32 m0, s46
	s_nop 0
	global_load_lds_dwordx4 v[222:223], off
	s_mov_b32 m0, s47
	s_nop 0
	global_load_lds_dwordx4 v[224:225], off
	s_waitcnt vmcnt(8)
	s_waitcnt lgkmcnt(0)
	s_barrier
	s_setprio 1
	s_waitcnt lgkmcnt(0)
	v_mfma_f32_16x16x32_bf16 v[62:65], v[156:159], v[188:191], v[62:65]
	v_mfma_f32_16x16x32_bf16 v[58:61], v[164:167], v[188:191], v[58:61]
	v_mfma_f32_16x16x32_bf16 v[46:49], v[156:159], v[196:199], v[46:49]
	v_mfma_f32_16x16x32_bf16 v[42:45], v[164:167], v[196:199], v[42:45]
	v_mfma_f32_16x16x32_bf16 v[30:33], v[156:159], v[204:207], v[30:33]
	v_mfma_f32_16x16x32_bf16 v[26:29], v[164:167], v[204:207], v[26:29]
	v_mfma_f32_16x16x32_bf16 v[14:17], v[156:159], v[212:215], v[14:17]
	v_mfma_f32_16x16x32_bf16 v[10:13], v[164:167], v[212:215], v[10:13]
	v_mfma_f32_16x16x32_bf16 v[62:65], v[160:163], v[192:195], v[62:65]
	v_mfma_f32_16x16x32_bf16 v[58:61], v[168:171], v[192:195], v[58:61]
	v_mfma_f32_16x16x32_bf16 v[46:49], v[160:163], v[200:203], v[46:49]
	v_mfma_f32_16x16x32_bf16 v[42:45], v[168:171], v[200:203], v[42:45]
	v_mfma_f32_16x16x32_bf16 v[30:33], v[160:163], v[208:211], v[30:33]
	v_mfma_f32_16x16x32_bf16 v[26:29], v[168:171], v[208:211], v[26:29]
	v_mfma_f32_16x16x32_bf16 v[14:17], v[160:163], v[216:219], v[14:17]
	v_mfma_f32_16x16x32_bf16 v[10:13], v[168:171], v[216:219], v[10:13]
	s_setprio 0
	s_setprio 1
	v_mfma_f32_16x16x32_bf16 v[54:57], v[172:175], v[188:191], v[54:57]
	v_mfma_f32_16x16x32_bf16 v[50:53], v[180:183], v[188:191], v[50:53]
	v_mfma_f32_16x16x32_bf16 v[38:41], v[172:175], v[196:199], v[38:41]
	v_mfma_f32_16x16x32_bf16 v[34:37], v[180:183], v[196:199], v[34:37]
	v_mfma_f32_16x16x32_bf16 v[22:25], v[172:175], v[204:207], v[22:25]
	v_mfma_f32_16x16x32_bf16 v[18:21], v[180:183], v[204:207], v[18:21]
	v_mfma_f32_16x16x32_bf16 v[6:9], v[172:175], v[212:215], v[6:9]
	v_mfma_f32_16x16x32_bf16 v[2:5], v[180:183], v[212:215], v[2:5]
	v_mfma_f32_16x16x32_bf16 v[54:57], v[176:179], v[192:195], v[54:57]
	v_mfma_f32_16x16x32_bf16 v[50:53], v[184:187], v[192:195], v[50:53]
	v_mfma_f32_16x16x32_bf16 v[38:41], v[176:179], v[200:203], v[38:41]
	v_mfma_f32_16x16x32_bf16 v[34:37], v[184:187], v[200:203], v[34:37]
	v_mfma_f32_16x16x32_bf16 v[22:25], v[176:179], v[208:211], v[22:25]
	v_mfma_f32_16x16x32_bf16 v[18:21], v[184:187], v[208:211], v[18:21]
	v_mfma_f32_16x16x32_bf16 v[6:9], v[176:179], v[216:219], v[6:9]
	v_mfma_f32_16x16x32_bf16 v[2:5], v[184:187], v[216:219], v[2:5]
	s_setprio 0
	s_barrier
	s_add_i32 s70, 0, 0x18000
	v_add_u32_e32 v146, s70, v149
	s_add_i32 s71, 0, 0x1c000
	ds_read_b128 v[156:159], v146
	ds_read_b128 v[160:163], v146 offset:1024
	ds_read_b128 v[164:167], v146 offset:2048
	ds_read_b128 v[168:171], v146 offset:3072
	v_add_u32_e32 v146, s71, v149
	ds_read_b128 v[172:175], v146
	ds_read_b128 v[176:179], v146 offset:1024
	ds_read_b128 v[180:183], v146 offset:2048
	ds_read_b128 v[184:187], v146 offset:3072
	s_add_u32 s8, s8, 0x40000
	s_addc_u32 s9, s9, 0
	s_mov_b32 m0, s48
	v_lshl_add_u64 v[226:227], s[8:9], 0, v[130:131]
	ds_read_b128 v[188:191], v155 offset:32768
	ds_read_b128 v[192:195], v155 offset:33792
	ds_read_b128 v[196:199], v155 offset:34816
	ds_read_b128 v[200:203], v155 offset:35840
	ds_read_b128 v[204:207], v155 offset:36864
	ds_read_b128 v[208:211], v155 offset:37888
	ds_read_b128 v[212:215], v155 offset:38912
	ds_read_b128 v[216:219], v155 offset:39936
	global_load_lds_dwordx4 v[226:227], off
	v_lshl_add_u64 v[226:227], s[8:9], 0, v[134:135]
	s_mov_b32 m0, s49
	s_nop 0
	global_load_lds_dwordx4 v[226:227], off
	s_waitcnt vmcnt(8)
	s_waitcnt lgkmcnt(0)
	s_barrier
	s_setprio 1
	s_waitcnt lgkmcnt(0)
	v_mfma_f32_16x16x32_bf16 v[126:129], v[156:159], v[188:191], v[126:129]
	v_mfma_f32_16x16x32_bf16 v[122:125], v[164:167], v[188:191], v[122:125]
	v_mfma_f32_16x16x32_bf16 v[110:113], v[156:159], v[196:199], v[110:113]
	v_mfma_f32_16x16x32_bf16 v[106:109], v[164:167], v[196:199], v[106:109]
	v_mfma_f32_16x16x32_bf16 v[94:97], v[156:159], v[204:207], v[94:97]
	v_mfma_f32_16x16x32_bf16 v[90:93], v[164:167], v[204:207], v[90:93]
	v_mfma_f32_16x16x32_bf16 v[78:81], v[156:159], v[212:215], v[78:81]
	v_mfma_f32_16x16x32_bf16 v[74:77], v[164:167], v[212:215], v[74:77]
	v_mfma_f32_16x16x32_bf16 v[126:129], v[160:163], v[192:195], v[126:129]
	v_mfma_f32_16x16x32_bf16 v[122:125], v[168:171], v[192:195], v[122:125]
	v_mfma_f32_16x16x32_bf16 v[110:113], v[160:163], v[200:203], v[110:113]
	v_mfma_f32_16x16x32_bf16 v[106:109], v[168:171], v[200:203], v[106:109]
	v_mfma_f32_16x16x32_bf16 v[94:97], v[160:163], v[208:211], v[94:97]
	v_mfma_f32_16x16x32_bf16 v[90:93], v[168:171], v[208:211], v[90:93]
	v_mfma_f32_16x16x32_bf16 v[78:81], v[160:163], v[216:219], v[78:81]
	v_mfma_f32_16x16x32_bf16 v[74:77], v[168:171], v[216:219], v[74:77]
	s_setprio 0
	s_setprio 1
	v_mfma_f32_16x16x32_bf16 v[118:121], v[172:175], v[188:191], v[118:121]
	v_mfma_f32_16x16x32_bf16 v[114:117], v[180:183], v[188:191], v[114:117]
	v_mfma_f32_16x16x32_bf16 v[102:105], v[172:175], v[196:199], v[102:105]
	v_mfma_f32_16x16x32_bf16 v[98:101], v[180:183], v[196:199], v[98:101]
	v_mfma_f32_16x16x32_bf16 v[86:89], v[172:175], v[204:207], v[86:89]
	v_mfma_f32_16x16x32_bf16 v[82:85], v[180:183], v[204:207], v[82:85]
	v_mfma_f32_16x16x32_bf16 v[70:73], v[172:175], v[212:215], v[70:73]
	v_mfma_f32_16x16x32_bf16 v[66:69], v[180:183], v[212:215], v[66:69]
	v_mfma_f32_16x16x32_bf16 v[118:121], v[176:179], v[192:195], v[118:121]
	v_mfma_f32_16x16x32_bf16 v[114:117], v[184:187], v[192:195], v[114:117]
	v_mfma_f32_16x16x32_bf16 v[102:105], v[176:179], v[200:203], v[102:105]
	v_mfma_f32_16x16x32_bf16 v[98:101], v[184:187], v[200:203], v[98:101]
	v_mfma_f32_16x16x32_bf16 v[86:89], v[176:179], v[208:211], v[86:89]
	v_mfma_f32_16x16x32_bf16 v[82:85], v[184:187], v[208:211], v[82:85]
	v_mfma_f32_16x16x32_bf16 v[70:73], v[176:179], v[216:219], v[70:73]
	v_mfma_f32_16x16x32_bf16 v[66:69], v[184:187], v[216:219], v[66:69]
	s_setprio 0
	s_barrier
	s_cmp_lg_u32 s12, s0
	s_cbranch_scc1 .Lmy_p8_nostat
	v_add_f32_e32 v236, v228, v229
	v_add_f32_e32 v240, v230, v231
	v_add_f32_e32 v237, v232, v233
	v_add_f32_e32 v241, v234, v235
	v_add_f32_e32 v236, v236, v240
	v_add_f32_e32 v237, v237, v241
	v_mov_b32_e32 v240, 0x20800
	v_lshl_add_u32 v240, v0, 3, v240
	ds_write_b64 v240, v[236:237]
.Lmy_p8_nostat:
	s_add_i32 s8, s70, s45
	v_lshl_add_u64 v[138:139], v[138:139], 0, s[20:21]
	s_mov_b32 m0, s8
	ds_read_b128 v[188:191], v155 offset:49152
	ds_read_b128 v[192:195], v155 offset:50176
	ds_read_b128 v[196:199], v155 offset:51200
	ds_read_b128 v[200:203], v155 offset:52224
	ds_read_b128 v[204:207], v155 offset:53248
	ds_read_b128 v[208:211], v155 offset:54272
	ds_read_b128 v[212:215], v155 offset:55296
	ds_read_b128 v[216:219], v155 offset:56320
	global_load_lds_dwordx4 v[138:139], off
	s_add_i32 m0, s8, 0x2000
	s_add_u32 s6, s6, 0x10080
	v_lshl_add_u64 v[138:139], v[220:221], 0, s[20:21]
	s_addc_u32 s7, s7, 0
	s_add_i32 s8, s71, s45
	global_load_lds_dwordx4 v[138:139], off
	v_lshl_add_u64 v[138:139], s[6:7], 0, v[132:133]
	s_mov_b32 m0, s8
	s_nop 0
	global_load_lds_dwordx4 v[138:139], off
	v_lshl_add_u64 v[138:139], s[6:7], 0, v[136:137]
	s_add_i32 m0, s8, 0x2000
	s_nop 0
	global_load_lds_dwordx4 v[138:139], off
	v_lshl_add_u64 v[138:139], v[222:223], 0, s[20:21]
	s_mov_b32 m0, s53
	s_nop 0
	global_load_lds_dwordx4 v[138:139], off
	v_lshl_add_u64 v[138:139], v[224:225], 0, s[20:21]
	s_mov_b32 m0, s54
	s_nop 0
	global_load_lds_dwordx4 v[138:139], off
	s_waitcnt vmcnt(8)
	s_waitcnt lgkmcnt(0)
	s_barrier
	s_setprio 1
	s_waitcnt lgkmcnt(0)
	v_mfma_f32_16x16x32_bf16 v[62:65], v[156:159], v[188:191], v[62:65]
	v_mfma_f32_16x16x32_bf16 v[58:61], v[164:167], v[188:191], v[58:61]
	v_mfma_f32_16x16x32_bf16 v[46:49], v[156:159], v[196:199], v[46:49]
	v_mfma_f32_16x16x32_bf16 v[42:45], v[164:167], v[196:199], v[42:45]
	v_mfma_f32_16x16x32_bf16 v[30:33], v[156:159], v[204:207], v[30:33]
	v_mfma_f32_16x16x32_bf16 v[26:29], v[164:167], v[204:207], v[26:29]
	v_mfma_f32_16x16x32_bf16 v[14:17], v[156:159], v[212:215], v[14:17]
	v_mfma_f32_16x16x32_bf16 v[10:13], v[164:167], v[212:215], v[10:13]
	v_mfma_f32_16x16x32_bf16 v[62:65], v[160:163], v[192:195], v[62:65]
	v_mfma_f32_16x16x32_bf16 v[58:61], v[168:171], v[192:195], v[58:61]
	v_mfma_f32_16x16x32_bf16 v[46:49], v[160:163], v[200:203], v[46:49]
	v_mfma_f32_16x16x32_bf16 v[42:45], v[168:171], v[200:203], v[42:45]
	v_mfma_f32_16x16x32_bf16 v[30:33], v[160:163], v[208:211], v[30:33]
	v_mfma_f32_16x16x32_bf16 v[26:29], v[168:171], v[208:211], v[26:29]
	v_mfma_f32_16x16x32_bf16 v[14:17], v[160:163], v[216:219], v[14:17]
	v_mfma_f32_16x16x32_bf16 v[10:13], v[168:171], v[216:219], v[10:13]
	s_setprio 0
	s_setprio 1
	v_mfma_f32_16x16x32_bf16 v[54:57], v[172:175], v[188:191], v[54:57]
	v_mfma_f32_16x16x32_bf16 v[50:53], v[180:183], v[188:191], v[50:53]
	v_mfma_f32_16x16x32_bf16 v[38:41], v[172:175], v[196:199], v[38:41]
	v_mfma_f32_16x16x32_bf16 v[34:37], v[180:183], v[196:199], v[34:37]
	v_mfma_f32_16x16x32_bf16 v[22:25], v[172:175], v[204:207], v[22:25]
	v_mfma_f32_16x16x32_bf16 v[18:21], v[180:183], v[204:207], v[18:21]
	v_mfma_f32_16x16x32_bf16 v[6:9], v[172:175], v[212:215], v[6:9]
	v_mfma_f32_16x16x32_bf16 v[2:5], v[180:183], v[212:215], v[2:5]
	v_mfma_f32_16x16x32_bf16 v[54:57], v[176:179], v[192:195], v[54:57]
	v_mfma_f32_16x16x32_bf16 v[50:53], v[184:187], v[192:195], v[50:53]
	v_mfma_f32_16x16x32_bf16 v[38:41], v[176:179], v[200:203], v[38:41]
	v_mfma_f32_16x16x32_bf16 v[34:37], v[184:187], v[200:203], v[34:37]
	v_mfma_f32_16x16x32_bf16 v[22:25], v[176:179], v[208:211], v[22:25]
	v_mfma_f32_16x16x32_bf16 v[18:21], v[184:187], v[208:211], v[18:21]
	v_mfma_f32_16x16x32_bf16 v[6:9], v[176:179], v[216:219], v[6:9]
	v_mfma_f32_16x16x32_bf16 v[2:5], v[184:187], v[216:219], v[2:5]
	s_setprio 0
	s_barrier
	s_add_i32 s63, s63, 2
	s_add_u32 s64, s64, 0x100
	s_addc_u32 s65, s65, 0
	s_add_u32 s66, s66, 0x100
	s_addc_u32 s67, s67, 0
	s_add_u32 s0, s0, 0xffffff00
	s_addc_u32 s1, s1, -1
	v_lshl_add_u64 v[142:143], v[142:143], 0, s[24:25]
	s_cmp_gt_u32 s63, 13
	v_lshl_add_u64 v[144:145], v[144:145], 0, s[24:25]
	s_cbranch_scc0 .LBB0_971
	s_add_u32 s0, s61, 0x40080
	s_addc_u32 s1, s37, 0
	s_mov_b32 m0, s69
	v_lshl_add_u64 v[138:139], s[0:1], 0, v[130:131]
	global_load_lds_dwordx4 v[138:139], off
	v_lshl_add_u64 v[138:139], s[0:1], 0, v[134:135]
	s_mov_b32 m0, s68
	s_and_b64 vcc, exec, s[22:23]
	global_load_lds_dwordx4 v[138:139], off
	s_cbranch_vccz .LBB0_974
	s_barrier
.LBB0_974:
	v_add_u32_e32 v236, s52, v1
	v_lshlrev_b32_e32 v236, 4, v236
	v_lshl_add_u32 v236, v147, 2, v236
	v_add_u32_e32 v236, 0x20800, v236
	ds_read_b32 v228, v236
	ds_read_b32 v229, v236 offset:256
	ds_read_b32 v230, v236 offset:512
	ds_read_b32 v231, v236 offset:768
	ds_read_b32 v232, v236 offset:2048
	ds_read_b32 v233, v236 offset:2304
	ds_read_b32 v234, v236 offset:2560
	ds_read_b32 v235, v236 offset:2816
	s_lshl_b32 s1, s4, 8
	v_mov_b32_e32 v158, v147
	v_mov_b32_e32 v131, v1
	s_add_i32 s1, s1, s52
	v_mov_b64_e32 v[188:189], s[30:31]
	v_add_u32_e32 v138, s1, v131
	v_ashrrev_i32_e32 v159, 31, v158
	v_ashrrev_i32_e32 v139, 31, v138
	v_lshl_add_u64 v[142:143], v[158:159], 4, s[16:17]
	v_lshlrev_b64 v[138:139], 6, v[138:139]
	v_lshl_add_u64 v[138:139], v[142:143], 0, v[138:139]
	v_add_co_u32_e32 v138, vcc, s50, v138
	s_lshl_b32 s0, s5, 8
	s_nop 0
	v_addc_co_u32_e32 v139, vcc, 0, v139, vcc
	s_or_b32 s0, s0, s55
	v_lshlrev_b32_e32 v158, 3, v158
	v_ashrrev_i32_e32 v159, 31, v158
	s_waitcnt lgkmcnt(0)
	v_mov_b32_e32 v138, v143
	v_mov_b32_e32 v139, v144
	v_mov_b32_e32 v143, v145
	v_mov_b32_e32 v144, v161
	v_mov_b32_e32 v145, v162
	v_mov_b32_e32 v161, v163
	v_mov_b32_e32 v156, v165
	v_mov_b32_e32 v157, v166
	v_mov_b32_e32 v165, v167
	v_mov_b32_e32 v162, v169
	v_mov_b32_e32 v163, v170
	v_mov_b32_e32 v169, v171
	v_pk_add_f32 v[138:139], v[138:139], v[142:143]
	v_pk_add_f32 v[142:143], v[144:145], v[160:161]
	v_pk_add_f32 v[144:145], v[156:157], v[164:165]
	v_pk_add_f32 v[156:157], v[162:163], v[168:169]
	v_mov_b32_e32 v138, v228
	v_mov_b32_e32 v139, v228
	v_mov_b32_e32 v142, v229
	v_mov_b32_e32 v143, v229
	v_mov_b32_e32 v144, v230
	v_mov_b32_e32 v145, v230
	v_mov_b32_e32 v156, v231
	v_mov_b32_e32 v157, v231
	v_mov_b32_e32 v133, v138
	v_mov_b32_e32 v135, v142
	v_mov_b32_e32 v143, v144
	v_mov_b32_e32 v145, v156
	v_permlane16_swap_b32_e32 v138, v133
	v_permlane16_swap_b32_e32 v142, v135
	v_permlane16_swap_b32_e32 v144, v143
	v_permlane16_swap_b32_e32 v156, v145
	v_add_f32_e32 v139, v138, v133
	v_add_f32_e32 v138, v142, v135
	v_add_f32_e32 v143, v144, v143
	v_add_f32_e32 v142, v156, v145
	v_mov_b32_e32 v145, v139
	v_mov_b32_e32 v144, v138
	v_mov_b32_e32 v157, v143
	v_mov_b32_e32 v156, v142
	v_permlane32_swap_b32_e32 v139, v145
	v_permlane32_swap_b32_e32 v138, v144
	v_permlane32_swap_b32_e32 v143, v157
	v_permlane32_swap_b32_e32 v142, v156
	v_pk_add_f32 v[138:139], v[138:139], v[144:145]
	v_pk_add_f32 v[142:143], v[142:143], v[156:157]
	v_pk_fma_f32 v[138:139], v[138:139], s[28:29], v[188:189] op_sel_hi:[1,0,0]
	v_pk_fma_f32 v[142:143], v[142:143], s[28:29], v[188:189] op_sel_hi:[1,0,0]
	v_mul_f32_e32 v135, 0x4b800000, v138
	v_mul_f32_e32 v144, 0x4b800000, v143
	v_cmp_gt_f32_e64 s[4:5], s59, v138
	v_cmp_gt_f32_e64 s[6:7], s59, v143
	v_mul_f32_e32 v133, 0x4b800000, v139
	v_mul_f32_e32 v145, 0x4b800000, v142
	v_cmp_gt_f32_e32 vcc, s59, v139
	v_cndmask_b32_e64 v135, v138, v135, s[4:5]
	v_cndmask_b32_e64 v138, v143, v144, s[6:7]
	v_cmp_gt_f32_e64 s[8:9], s59, v142
	v_cndmask_b32_e32 v133, v139, v133, vcc
	v_rsq_f32_e32 v135, v135
	v_cndmask_b32_e64 v139, v142, v145, s[8:9]
	v_rsq_f32_e32 v142, v138
	v_rsq_f32_e32 v133, v133
	v_mov_b32_e32 v160, v173
	v_mov_b32_e32 v161, v174
	v_mov_b32_e32 v173, v175
	v_pk_add_f32 v[162:163], v[160:161], v[172:173]
	v_mul_f32_e32 v143, 0x45800000, v135
	v_mul_f32_e32 v144, 0x45800000, v142
	v_mul_f32_e32 v138, 0x45800000, v133
	v_cndmask_b32_e64 v160, v135, v143, s[4:5]
	v_cndmask_b32_e64 v156, v142, v144, s[6:7]
	v_mov_b32_e32 v142, v232
	v_mov_b32_e32 v143, v232
	v_mov_b32_e32 v162, v177
	v_mov_b32_e32 v163, v178
	v_mov_b32_e32 v177, v179
	v_cndmask_b32_e32 v138, v133, v138, vcc
	v_mov_b32_e32 v133, v142
	v_pk_add_f32 v[162:163], v[162:163], v[176:177]
	s_nop 0
	v_permlane16_swap_b32_e32 v142, v133
	v_mov_b32_e32 v162, v233
	v_mov_b32_e32 v163, v233
	v_add_f32_e32 v143, v142, v133
	v_mov_b32_e32 v133, v162
	s_nop 1
	v_permlane16_swap_b32_e32 v162, v133
	v_add_f32_e32 v142, v162, v133
	v_mov_b32_e32 v145, v143
	v_mov_b32_e32 v144, v142
	s_nop 0
	v_permlane32_swap_b32_e32 v143, v145
	v_permlane32_swap_b32_e32 v142, v144
	v_pk_add_f32 v[142:143], v[142:143], v[144:145]
	v_rsq_f32_e32 v139, v139
	v_pk_fma_f32 v[142:143], v[142:143], s[28:29], v[188:189] op_sel_hi:[1,0,0]
	v_mov_b32_e32 v162, v185
	v_mul_f32_e32 v133, 0x4b800000, v143
	v_cmp_gt_f32_e32 vcc, s59, v143
	v_mul_f32_e32 v135, 0x4b800000, v142
	v_cmp_gt_f32_e64 s[4:5], s59, v142
	v_cndmask_b32_e32 v133, v143, v133, vcc
	v_rsq_f32_e32 v133, v133
	v_cndmask_b32_e64 v135, v142, v135, s[4:5]
	v_mov_b32_e32 v142, v181
	v_mov_b32_e32 v143, v182
	v_mov_b32_e32 v181, v183
	v_mul_f32_e32 v146, 0x45800000, v139
	v_pk_add_f32 v[142:143], v[142:143], v[180:181]
	v_cndmask_b32_e64 v154, v139, v146, s[8:9]
	v_mul_f32_e32 v139, 0x45800000, v133
	v_mov_b32_e32 v142, v234
	v_mov_b32_e32 v143, v234
	v_mov_b32_e32 v163, v186
	v_mov_b32_e32 v185, v187
	v_cndmask_b32_e32 v152, v133, v139, vcc
	v_mov_b32_e32 v139, v142
	v_pk_add_f32 v[162:163], v[162:163], v[184:185]
	s_nop 0
	v_permlane16_swap_b32_e32 v142, v139
	v_mov_b32_e32 v162, v235
	v_mov_b32_e32 v163, v235
	v_add_f32_e32 v143, v142, v139
	v_mov_b32_e32 v139, v162
	s_nop 1
	v_permlane16_swap_b32_e32 v162, v139
	v_add_f32_e32 v142, v162, v139
	v_mov_b32_e32 v145, v143
	v_mov_b32_e32 v144, v142
	s_nop 0
	v_permlane32_swap_b32_e32 v143, v145
	v_permlane32_swap_b32_e32 v142, v144
	v_pk_add_f32 v[142:143], v[142:143], v[144:145]
	v_rsq_f32_e32 v135, v135
	v_pk_fma_f32 v[142:143], v[142:143], s[28:29], v[188:189] op_sel_hi:[1,0,0]
	v_pk_mul_f32 v[106:107], v[106:107], v[160:161] op_sel_hi:[1,0]
	v_mul_f32_e32 v139, 0x4b800000, v143
	v_cmp_gt_f32_e32 vcc, s59, v143
	v_pk_mul_f32 v[104:105], v[104:105], v[160:161] op_sel_hi:[1,0]
	v_pk_mul_f32 v[102:103], v[102:103], v[160:161] op_sel_hi:[1,0]
	v_cndmask_b32_e32 v139, v143, v139, vcc
	v_rsq_f32_e32 v139, v139
	v_pk_mul_f32 v[98:99], v[98:99], v[160:161] op_sel_hi:[1,0]
	v_mul_f32_e32 v133, 0x45800000, v135
	v_mul_f32_e32 v143, 0x4b800000, v142
	v_pk_mul_f32 v[124:125], v[124:125], v[138:139] op_sel_hi:[1,0]
	v_pk_mul_f32 v[122:123], v[122:123], v[138:139] op_sel_hi:[1,0]
	v_pk_mul_f32 v[116:117], v[116:117], v[138:139] op_sel_hi:[1,0]
	v_pk_mul_f32 v[114:115], v[114:115], v[138:139] op_sel_hi:[1,0]
	v_cmp_gt_f32_e64 s[6:7], s59, v142
	v_pk_mul_f32 v[128:129], v[128:129], v[138:139] op_sel_hi:[1,0]
	v_pk_mul_f32 v[126:127], v[126:127], v[138:139] op_sel_hi:[1,0]
	v_max_f32_e32 v122, 0, v122
	v_max_f32_e32 v123, 0, v123
	v_max_f32_e32 v124, 0, v124
	v_max_f32_e32 v125, 0, v125
	v_pk_mul_f32 v[120:121], v[120:121], v[138:139] op_sel_hi:[1,0]
	v_pk_mul_f32 v[118:119], v[118:119], v[138:139] op_sel_hi:[1,0]
	v_max_f32_e32 v114, 0, v114
	v_max_f32_e32 v115, 0, v115
	v_max_f32_e32 v116, 0, v116
	v_max_f32_e32 v117, 0, v117
	v_pk_mul_f32 v[112:113], v[112:113], v[160:161] op_sel_hi:[1,0]
	v_pk_mul_f32 v[110:111], v[110:111], v[160:161] op_sel_hi:[1,0]
	v_pk_mul_f32 v[108:109], v[108:109], v[160:161] op_sel_hi:[1,0]
	v_max_f32_e32 v106, 0, v106
	v_max_f32_e32 v107, 0, v107
	v_pk_mul_f32 v[100:101], v[100:101], v[160:161] op_sel_hi:[1,0]
	v_max_f32_e32 v102, 0, v102
	v_max_f32_e32 v98, 0, v98
	v_max_f32_e32 v103, 0, v103
	v_max_f32_e32 v99, 0, v99
	v_max_f32_e32 v104, 0, v104
	v_max_f32_e32 v105, 0, v105
	v_cndmask_b32_e64 v142, v142, v143, s[6:7]
	v_cndmask_b32_e64 v150, v135, v133, s[4:5]
	v_mul_f32_e32 v133, 0x45800000, v139
	v_max_f32_e32 v126, 0, v126
	v_max_f32_e32 v127, 0, v127
	v_pk_mul_f32 v[122:123], v[122:123], v[122:123]
	v_max_f32_e32 v128, 0, v128
	v_max_f32_e32 v129, 0, v129
	v_pk_mul_f32 v[124:125], v[124:125], v[124:125]
	v_max_f32_e32 v118, 0, v118
	v_max_f32_e32 v119, 0, v119
	v_pk_mul_f32 v[114:115], v[114:115], v[114:115]
	v_max_f32_e32 v120, 0, v120
	v_max_f32_e32 v121, 0, v121
	v_pk_mul_f32 v[116:117], v[116:117], v[116:117]
	v_max_f32_e32 v110, 0, v110
	v_max_f32_e32 v111, 0, v111
	v_pk_mul_f32 v[106:107], v[106:107], v[106:107]
	v_max_f32_e32 v112, 0, v112
	v_max_f32_e32 v108, 0, v108
	v_max_f32_e32 v113, 0, v113
	v_max_f32_e32 v109, 0, v109
	v_pk_mul_f32 v[102:103], v[102:103], v[102:103]
	v_pk_mul_f32 v[98:99], v[98:99], v[98:99]
	v_max_f32_e32 v100, 0, v100
	v_pk_mul_f32 v[104:105], v[104:105], v[104:105]
	v_max_f32_e32 v101, 0, v101
	v_pk_mul_f32 v[90:91], v[90:91], v[156:157] op_sel_hi:[1,0]
	v_pk_mul_f32 v[88:89], v[88:89], v[156:157] op_sel_hi:[1,0]
	v_pk_mul_f32 v[86:87], v[86:87], v[156:157] op_sel_hi:[1,0]
	v_pk_mul_f32 v[82:83], v[82:83], v[156:157] op_sel_hi:[1,0]
	v_rsq_f32_e32 v142, v142
	v_cndmask_b32_e32 v148, v139, v133, vcc
	v_cmp_gt_i32_e32 vcc, 8, v131
	v_pk_mul_f32 v[126:127], v[126:127], v[126:127]
	v_pk_mul_f32 v[128:129], v[128:129], v[128:129]
	v_cvt_pk_bf16_f32 v122, v122, v123
	v_cvt_pk_bf16_f32 v123, v124, v125
	v_pk_mul_f32 v[118:119], v[118:119], v[118:119]
	v_pk_mul_f32 v[120:121], v[120:121], v[120:121]
	v_cvt_pk_bf16_f32 v114, v114, v115
	v_cvt_pk_bf16_f32 v115, v116, v117
	v_pk_mul_f32 v[110:111], v[110:111], v[110:111]
	v_pk_mul_f32 v[112:113], v[112:113], v[112:113]
	v_pk_mul_f32 v[108:109], v[108:109], v[108:109]
	v_cvt_pk_bf16_f32 v106, v106, v107
	v_pk_mul_f32 v[100:101], v[100:101], v[100:101]
	v_cvt_pk_bf16_f32 v102, v102, v103
	v_cvt_pk_bf16_f32 v103, v104, v105
	v_cvt_pk_bf16_f32 v104, v98, v99
	v_pk_mul_f32 v[96:97], v[96:97], v[156:157] op_sel_hi:[1,0]
	v_pk_mul_f32 v[94:95], v[94:95], v[156:157] op_sel_hi:[1,0]
	v_pk_mul_f32 v[92:93], v[92:93], v[156:157] op_sel_hi:[1,0]
	v_max_f32_e32 v90, 0, v90
	v_max_f32_e32 v91, 0, v91
	v_pk_mul_f32 v[84:85], v[84:85], v[156:157] op_sel_hi:[1,0]
	v_max_f32_e32 v86, 0, v86
	v_max_f32_e32 v82, 0, v82
	v_max_f32_e32 v87, 0, v87
	v_max_f32_e32 v83, 0, v83
	v_max_f32_e32 v88, 0, v88
	v_max_f32_e32 v89, 0, v89
	v_and_or_b32 v144, v131, 7, s1
	v_cvt_pk_bf16_f32 v126, v126, v127
	v_cvt_pk_bf16_f32 v127, v128, v129
	v_cvt_pk_bf16_f32 v124, v118, v119
	v_cvt_pk_bf16_f32 v120, v120, v121
	v_cndmask_b32_e32 v116, v123, v115, vcc
	v_cndmask_b32_e32 v117, v122, v114, vcc
	v_cvt_pk_bf16_f32 v110, v110, v111
	v_cvt_pk_bf16_f32 v111, v112, v113
	v_cvt_pk_bf16_f32 v107, v108, v109
	v_cvt_pk_bf16_f32 v105, v100, v101
	v_cndmask_b32_e32 v99, v106, v104, vcc
	v_max_f32_e32 v94, 0, v94
	v_max_f32_e32 v95, 0, v95
	v_pk_mul_f32 v[90:91], v[90:91], v[90:91]
	v_max_f32_e32 v96, 0, v96
	v_max_f32_e32 v92, 0, v92
	v_max_f32_e32 v97, 0, v97
	v_max_f32_e32 v93, 0, v93
	v_pk_mul_f32 v[86:87], v[86:87], v[86:87]
	v_pk_mul_f32 v[82:83], v[82:83], v[82:83]
	v_max_f32_e32 v84, 0, v84
	v_pk_mul_f32 v[88:89], v[88:89], v[88:89]
	v_max_f32_e32 v85, 0, v85
	v_pk_mul_f32 v[74:75], v[74:75], v[154:155] op_sel_hi:[1,0]
	v_pk_mul_f32 v[72:73], v[72:73], v[154:155] op_sel_hi:[1,0]
	v_pk_mul_f32 v[70:71], v[70:71], v[154:155] op_sel_hi:[1,0]
	v_pk_mul_f32 v[66:67], v[66:67], v[154:155] op_sel_hi:[1,0]
	v_cndmask_b32_e32 v118, v127, v120, vcc
	v_cndmask_b32_e32 v119, v126, v124, vcc
	v_mov_b32_dpp v128, v117 row_ror:8 row_mask:0xf bank_mask:0xf bound_ctrl:1
	v_mov_b32_dpp v129, v116 row_ror:8 row_mask:0xf bank_mask:0xf bound_ctrl:1
	v_ashrrev_i32_e32 v145, 31, v144
	v_cndmask_b32_e32 v98, v107, v105, vcc
	v_cndmask_b32_e32 v100, v111, v103, vcc
	v_mov_b32_dpp v112, v99 row_ror:8 row_mask:0xf bank_mask:0xf bound_ctrl:1
	v_pk_mul_f32 v[94:95], v[94:95], v[94:95]
	v_pk_mul_f32 v[96:97], v[96:97], v[96:97]
	v_pk_mul_f32 v[92:93], v[92:93], v[92:93]
	v_cvt_pk_bf16_f32 v90, v90, v91
	v_pk_mul_f32 v[84:85], v[84:85], v[84:85]
	v_cvt_pk_bf16_f32 v86, v86, v87
	v_cvt_pk_bf16_f32 v87, v88, v89
	v_cvt_pk_bf16_f32 v88, v82, v83
	v_pk_mul_f32 v[80:81], v[80:81], v[154:155] op_sel_hi:[1,0]
	v_pk_mul_f32 v[78:79], v[78:79], v[154:155] op_sel_hi:[1,0]
	v_pk_mul_f32 v[76:77], v[76:77], v[154:155] op_sel_hi:[1,0]
	v_max_f32_e32 v74, 0, v74
	v_max_f32_e32 v75, 0, v75
	v_pk_mul_f32 v[68:69], v[68:69], v[154:155] op_sel_hi:[1,0]
	v_max_f32_e32 v70, 0, v70
	v_max_f32_e32 v66, 0, v66
	v_max_f32_e32 v71, 0, v71
	v_max_f32_e32 v67, 0, v67
	v_max_f32_e32 v72, 0, v72
	v_max_f32_e32 v73, 0, v73
	s_ashr_i32 s1, s0, 31
	v_mov_b32_dpp v125, v119 row_ror:8 row_mask:0xf bank_mask:0xf bound_ctrl:1
	v_mov_b32_dpp v121, v118 row_ror:8 row_mask:0xf bank_mask:0xf bound_ctrl:1
	v_cndmask_b32_e32 v119, v129, v123, vcc
	v_cndmask_b32_e32 v118, v128, v122, vcc
	v_cndmask_b32_e32 v123, v115, v129, vcc
	v_cndmask_b32_e32 v122, v114, v128, vcc
	v_lshlrev_b64 v[114:115], 13, v[144:145]
	v_cndmask_b32_e32 v101, v110, v102, vcc
	v_mov_b32_dpp v109, v100 row_ror:8 row_mask:0xf bank_mask:0xf bound_ctrl:1
	v_mov_b32_dpp v113, v98 row_ror:8 row_mask:0xf bank_mask:0xf bound_ctrl:1
	v_cndmask_b32_e32 v100, v112, v106, vcc
	v_or_b32_e32 v106, 16, v144
	v_cvt_pk_bf16_f32 v94, v94, v95
	v_cvt_pk_bf16_f32 v95, v96, v97
	v_cvt_pk_bf16_f32 v91, v92, v93
	v_cvt_pk_bf16_f32 v89, v84, v85
	v_cndmask_b32_e32 v83, v90, v88, vcc
	v_max_f32_e32 v78, 0, v78
	v_max_f32_e32 v79, 0, v79
	v_pk_mul_f32 v[74:75], v[74:75], v[74:75]
	v_max_f32_e32 v80, 0, v80
	v_max_f32_e32 v76, 0, v76
	v_max_f32_e32 v81, 0, v81
	v_max_f32_e32 v77, 0, v77
	v_pk_mul_f32 v[70:71], v[70:71], v[70:71]
	v_pk_mul_f32 v[66:67], v[66:67], v[66:67]
	v_max_f32_e32 v68, 0, v68
	v_pk_mul_f32 v[72:73], v[72:73], v[72:73]
	v_max_f32_e32 v69, 0, v69
	v_mul_f32_e32 v133, 0x45800000, v142
	v_lshl_add_u64 v[114:115], s[18:19], 0, v[114:115]
	s_lshl_b64 s[0:1], s[0:1], 1
	v_mov_b32_dpp v108, v101 row_ror:8 row_mask:0xf bank_mask:0xf bound_ctrl:1
	v_cndmask_b32_e32 v101, v113, v107, vcc
	v_ashrrev_i32_e32 v107, 31, v106
	v_cndmask_b32_e32 v82, v91, v89, vcc
	v_cndmask_b32_e32 v84, v95, v87, vcc
	v_mov_b32_dpp v96, v83 row_ror:8 row_mask:0xf bank_mask:0xf bound_ctrl:1
	v_pk_mul_f32 v[78:79], v[78:79], v[78:79]
	v_pk_mul_f32 v[80:81], v[80:81], v[80:81]
	v_pk_mul_f32 v[76:77], v[76:77], v[76:77]
	v_cvt_pk_bf16_f32 v74, v74, v75
	v_pk_mul_f32 v[68:69], v[68:69], v[68:69]
	v_cvt_pk_bf16_f32 v70, v70, v71
	v_cvt_pk_bf16_f32 v71, v72, v73
	v_cvt_pk_bf16_f32 v72, v66, v67
	v_cndmask_b32_e64 v146, v142, v133, s[6:7]
	v_cndmask_b32_e64 v142, 64, 0, vcc
	v_mov_b32_e32 v143, v137
	v_lshl_add_u64 v[114:115], v[114:115], 0, s[0:1]
	v_lshlrev_b64 v[106:107], 13, v[106:107]
	v_cndmask_b32_e32 v85, v94, v86, vcc
	v_mov_b32_dpp v93, v84 row_ror:8 row_mask:0xf bank_mask:0xf bound_ctrl:1
	v_mov_b32_dpp v97, v82 row_ror:8 row_mask:0xf bank_mask:0xf bound_ctrl:1
	v_cndmask_b32_e32 v84, v96, v90, vcc
	v_or_b32_e32 v90, 32, v144
	v_cvt_pk_bf16_f32 v78, v78, v79
	v_cvt_pk_bf16_f32 v79, v80, v81
	v_cvt_pk_bf16_f32 v75, v76, v77
	v_cvt_pk_bf16_f32 v73, v68, v69
	v_cndmask_b32_e32 v67, v74, v72, vcc
	v_cndmask_b32_e32 v117, v121, v127, vcc
	v_cndmask_b32_e32 v116, v125, v126, vcc
	v_cndmask_b32_e32 v121, v120, v121, vcc
	v_cndmask_b32_e32 v120, v124, v125, vcc
	v_lshl_add_u64 v[124:125], v[114:115], 0, v[142:143]
	v_lshlrev_b64 v[114:115], 1, v[158:159]
	v_lshl_add_u64 v[106:107], s[18:19], 0, v[106:107]
	v_mov_b32_dpp v92, v85 row_ror:8 row_mask:0xf bank_mask:0xf bound_ctrl:1
	v_cndmask_b32_e32 v85, v97, v91, vcc
	v_ashrrev_i32_e32 v91, 31, v90
	v_cndmask_b32_e32 v66, v75, v73, vcc
	v_cndmask_b32_e32 v68, v79, v71, vcc
	v_mov_b32_dpp v80, v67 row_ror:8 row_mask:0xf bank_mask:0xf bound_ctrl:1
	v_lshl_add_u64 v[124:125], v[124:125], 0, v[114:115]
	v_lshl_add_u64 v[106:107], v[106:107], 0, s[0:1]
	v_lshlrev_b64 v[90:91], 13, v[90:91]
	v_cndmask_b32_e32 v69, v78, v70, vcc
	v_mov_b32_dpp v77, v68 row_ror:8 row_mask:0xf bank_mask:0xf bound_ctrl:1
	v_mov_b32_dpp v81, v66 row_ror:8 row_mask:0xf bank_mask:0xf bound_ctrl:1
	v_cndmask_b32_e32 v68, v80, v74, vcc
	v_or_b32_e32 v74, 48, v144
	global_store_dwordx4 v[124:125], v[116:119], off
	v_lshl_add_u64 v[106:107], v[106:107], 0, v[142:143]
	v_lshl_add_u64 v[90:91], s[18:19], 0, v[90:91]
	v_add_co_u32_e64 v116, s[4:5], s51, v124
	v_mov_b32_dpp v76, v69 row_ror:8 row_mask:0xf bank_mask:0xf bound_ctrl:1
	v_cndmask_b32_e32 v69, v81, v75, vcc
	v_ashrrev_i32_e32 v75, 31, v74
	v_addc_co_u32_e64 v117, s[4:5], 0, v125, s[4:5]
	v_cndmask_b32_e32 v99, v109, v111, vcc
	v_cndmask_b32_e32 v98, v108, v110, vcc
	v_lshl_add_u64 v[106:107], v[106:107], 0, v[114:115]
	v_lshl_add_u64 v[90:91], v[90:91], 0, s[0:1]
	v_lshlrev_b64 v[74:75], 13, v[74:75]
	global_store_dwordx4 v[106:107], v[98:101], off
	v_lshl_add_u64 v[90:91], v[90:91], 0, v[142:143]
	v_lshl_add_u64 v[74:75], s[18:19], 0, v[74:75]
	v_add_co_u32_e64 v98, s[4:5], s51, v106
	v_cndmask_b32_e32 v83, v93, v95, vcc
	s_nop 0
	v_addc_co_u32_e64 v99, s[4:5], 0, v107, s[4:5]
	v_cndmask_b32_e32 v82, v92, v94, vcc
	v_lshl_add_u64 v[90:91], v[90:91], 0, v[114:115]
	v_lshl_add_u64 v[74:75], v[74:75], 0, s[0:1]
	global_store_dwordx4 v[90:91], v[82:85], off
	v_lshl_add_u64 v[74:75], v[74:75], 0, v[142:143]
	v_pk_mul_f32 v[60:61], v[60:61], v[152:153] op_sel_hi:[1,0]
	v_add_co_u32_e64 v82, s[4:5], s51, v90
	v_pk_mul_f32 v[58:59], v[58:59], v[152:153] op_sel_hi:[1,0]
	v_pk_mul_f32 v[56:57], v[56:57], v[152:153] op_sel_hi:[1,0]
	v_pk_mul_f32 v[54:55], v[54:55], v[152:153] op_sel_hi:[1,0]
	v_pk_mul_f32 v[52:53], v[52:53], v[152:153] op_sel_hi:[1,0]
	v_pk_mul_f32 v[50:51], v[50:51], v[152:153] op_sel_hi:[1,0]
	v_pk_mul_f32 v[42:43], v[42:43], v[150:151] op_sel_hi:[1,0]
	v_pk_mul_f32 v[40:41], v[40:41], v[150:151] op_sel_hi:[1,0]
	v_pk_mul_f32 v[38:39], v[38:39], v[150:151] op_sel_hi:[1,0]
	v_pk_mul_f32 v[34:35], v[34:35], v[150:151] op_sel_hi:[1,0]
	v_addc_co_u32_e64 v83, s[4:5], 0, v91, s[4:5]
	v_cndmask_b32_e32 v67, v77, v79, vcc
	v_cndmask_b32_e32 v66, v76, v78, vcc
	v_lshl_add_u64 v[74:75], v[74:75], 0, v[114:115]
	v_pk_mul_f32 v[64:65], v[64:65], v[152:153] op_sel_hi:[1,0]
	v_pk_mul_f32 v[62:63], v[62:63], v[152:153] op_sel_hi:[1,0]
	v_max_f32_e32 v58, 0, v58
	v_max_f32_e32 v59, 0, v59
	v_max_f32_e32 v60, 0, v60
	v_max_f32_e32 v61, 0, v61
	v_max_f32_e32 v54, 0, v54
	v_max_f32_e32 v50, 0, v50
	v_max_f32_e32 v55, 0, v55
	v_max_f32_e32 v51, 0, v51
	v_max_f32_e32 v56, 0, v56
	v_max_f32_e32 v52, 0, v52
	v_max_f32_e32 v57, 0, v57
	v_max_f32_e32 v53, 0, v53
	v_pk_mul_f32 v[48:49], v[48:49], v[150:151] op_sel_hi:[1,0]
	v_pk_mul_f32 v[46:47], v[46:47], v[150:151] op_sel_hi:[1,0]
	v_pk_mul_f32 v[44:45], v[44:45], v[150:151] op_sel_hi:[1,0]
	v_max_f32_e32 v42, 0, v42
	v_max_f32_e32 v43, 0, v43
	v_pk_mul_f32 v[36:37], v[36:37], v[150:151] op_sel_hi:[1,0]
	v_max_f32_e32 v38, 0, v38
	v_max_f32_e32 v34, 0, v34
	v_max_f32_e32 v39, 0, v39
	v_max_f32_e32 v35, 0, v35
	v_max_f32_e32 v40, 0, v40
	v_max_f32_e32 v41, 0, v41
	v_pk_mul_f32 v[10:11], v[10:11], v[146:147] op_sel_hi:[1,0]
	v_pk_mul_f32 v[8:9], v[8:9], v[146:147] op_sel_hi:[1,0]
	v_pk_mul_f32 v[6:7], v[6:7], v[146:147] op_sel_hi:[1,0]
	v_pk_mul_f32 v[2:3], v[2:3], v[146:147] op_sel_hi:[1,0]
	global_store_dwordx4 v[74:75], v[66:69], off
	v_max_f32_e32 v62, 0, v62
	v_max_f32_e32 v63, 0, v63
	v_add_co_u32_e64 v66, s[4:5], s51, v74
	v_pk_mul_f32 v[58:59], v[58:59], v[58:59]
	v_max_f32_e32 v64, 0, v64
	v_max_f32_e32 v65, 0, v65
	v_pk_mul_f32 v[60:61], v[60:61], v[60:61]
	v_pk_mul_f32 v[54:55], v[54:55], v[54:55]
	v_pk_mul_f32 v[50:51], v[50:51], v[50:51]
	v_pk_mul_f32 v[56:57], v[56:57], v[56:57]
	v_pk_mul_f32 v[52:53], v[52:53], v[52:53]
	v_max_f32_e32 v46, 0, v46
	v_max_f32_e32 v47, 0, v47
	v_pk_mul_f32 v[42:43], v[42:43], v[42:43]
	v_max_f32_e32 v48, 0, v48
	v_max_f32_e32 v44, 0, v44
	v_max_f32_e32 v49, 0, v49
	v_max_f32_e32 v45, 0, v45
	v_pk_mul_f32 v[38:39], v[38:39], v[38:39]
	v_pk_mul_f32 v[34:35], v[34:35], v[34:35]
	v_max_f32_e32 v36, 0, v36
	v_pk_mul_f32 v[40:41], v[40:41], v[40:41]
	v_max_f32_e32 v37, 0, v37
	v_pk_mul_f32 v[26:27], v[26:27], v[148:149] op_sel_hi:[1,0]
	v_pk_mul_f32 v[24:25], v[24:25], v[148:149] op_sel_hi:[1,0]
	v_pk_mul_f32 v[22:23], v[22:23], v[148:149] op_sel_hi:[1,0]
	v_pk_mul_f32 v[18:19], v[18:19], v[148:149] op_sel_hi:[1,0]
	v_pk_mul_f32 v[16:17], v[16:17], v[146:147] op_sel_hi:[1,0]
	v_pk_mul_f32 v[14:15], v[14:15], v[146:147] op_sel_hi:[1,0]
	v_pk_mul_f32 v[12:13], v[12:13], v[146:147] op_sel_hi:[1,0]
	v_max_f32_e32 v10, 0, v10
	v_max_f32_e32 v11, 0, v11
	v_pk_mul_f32 v[4:5], v[4:5], v[146:147] op_sel_hi:[1,0]
	v_max_f32_e32 v6, 0, v6
	v_max_f32_e32 v2, 0, v2
	v_max_f32_e32 v7, 0, v7
	v_max_f32_e32 v3, 0, v3
	v_max_f32_e32 v8, 0, v8
	v_max_f32_e32 v9, 0, v9
	v_cndmask_b32_e32 v73, v73, v81, vcc
	v_cndmask_b32_e32 v72, v72, v80, vcc
	v_cndmask_b32_e32 v71, v71, v77, vcc
	v_cndmask_b32_e32 v70, v70, v76, vcc
	v_addc_co_u32_e64 v67, s[4:5], 0, v75, s[4:5]
	v_pk_mul_f32 v[62:63], v[62:63], v[62:63]
	v_pk_mul_f32 v[64:65], v[64:65], v[64:65]
	v_cvt_pk_bf16_f32 v58, v58, v59
	v_cvt_pk_bf16_f32 v59, v60, v61
	v_cvt_pk_bf16_f32 v54, v54, v55
	v_cvt_pk_bf16_f32 v55, v56, v57
	v_cvt_pk_bf16_f32 v56, v50, v51
	v_cvt_pk_bf16_f32 v57, v52, v53
	v_pk_mul_f32 v[46:47], v[46:47], v[46:47]
	v_pk_mul_f32 v[48:49], v[48:49], v[48:49]
	v_pk_mul_f32 v[44:45], v[44:45], v[44:45]
	v_cvt_pk_bf16_f32 v42, v42, v43
	v_pk_mul_f32 v[36:37], v[36:37], v[36:37]
	v_cvt_pk_bf16_f32 v38, v38, v39
	v_cvt_pk_bf16_f32 v39, v40, v41
	v_cvt_pk_bf16_f32 v40, v34, v35
	v_pk_mul_f32 v[32:33], v[32:33], v[148:149] op_sel_hi:[1,0]
	v_pk_mul_f32 v[30:31], v[30:31], v[148:149] op_sel_hi:[1,0]
	v_pk_mul_f32 v[28:29], v[28:29], v[148:149] op_sel_hi:[1,0]
	v_max_f32_e32 v26, 0, v26
	v_max_f32_e32 v27, 0, v27
	v_pk_mul_f32 v[20:21], v[20:21], v[148:149] op_sel_hi:[1,0]
	v_max_f32_e32 v22, 0, v22
	v_max_f32_e32 v18, 0, v18
	v_max_f32_e32 v23, 0, v23
	v_max_f32_e32 v19, 0, v19
	v_max_f32_e32 v24, 0, v24
	v_max_f32_e32 v25, 0, v25
	v_max_f32_e32 v14, 0, v14
	v_max_f32_e32 v15, 0, v15
	v_pk_mul_f32 v[10:11], v[10:11], v[10:11]
	v_max_f32_e32 v16, 0, v16
	v_max_f32_e32 v12, 0, v12
	v_max_f32_e32 v17, 0, v17
	v_max_f32_e32 v13, 0, v13
	v_pk_mul_f32 v[6:7], v[6:7], v[6:7]
	v_pk_mul_f32 v[2:3], v[2:3], v[2:3]
	v_max_f32_e32 v4, 0, v4
	v_pk_mul_f32 v[8:9], v[8:9], v[8:9]
	v_max_f32_e32 v5, 0, v5
	global_store_dwordx4 v[66:67], v[70:73], off
	v_add_u32_e32 v66, 0x80, v144
	v_cvt_pk_bf16_f32 v62, v62, v63
	v_cvt_pk_bf16_f32 v63, v64, v65
	v_cndmask_b32_e32 v50, v59, v57, vcc
	v_cndmask_b32_e32 v51, v58, v56, vcc
	v_cvt_pk_bf16_f32 v46, v46, v47
	v_cvt_pk_bf16_f32 v47, v48, v49
	v_cvt_pk_bf16_f32 v43, v44, v45
	v_cvt_pk_bf16_f32 v41, v36, v37
	v_cndmask_b32_e32 v35, v42, v40, vcc
	v_max_f32_e32 v30, 0, v30
	v_max_f32_e32 v31, 0, v31
	v_pk_mul_f32 v[26:27], v[26:27], v[26:27]
	v_max_f32_e32 v32, 0, v32
	v_max_f32_e32 v28, 0, v28
	v_max_f32_e32 v33, 0, v33
	v_max_f32_e32 v29, 0, v29
	v_pk_mul_f32 v[22:23], v[22:23], v[22:23]
	v_pk_mul_f32 v[18:19], v[18:19], v[18:19]
	v_max_f32_e32 v20, 0, v20
	v_pk_mul_f32 v[24:25], v[24:25], v[24:25]
	v_max_f32_e32 v21, 0, v21
	v_pk_mul_f32 v[14:15], v[14:15], v[14:15]
	v_pk_mul_f32 v[16:17], v[16:17], v[16:17]
	v_pk_mul_f32 v[12:13], v[12:13], v[12:13]
	v_cvt_pk_bf16_f32 v10, v10, v11
	v_pk_mul_f32 v[4:5], v[4:5], v[4:5]
	v_cvt_pk_bf16_f32 v6, v6, v7
	v_cvt_pk_bf16_f32 v7, v8, v9
	v_cvt_pk_bf16_f32 v8, v2, v3
	v_cndmask_b32_e32 v52, v63, v55, vcc
	v_cndmask_b32_e32 v53, v62, v54, vcc
	v_mov_b32_dpp v64, v51 row_ror:8 row_mask:0xf bank_mask:0xf bound_ctrl:1
	v_mov_b32_dpp v65, v50 row_ror:8 row_mask:0xf bank_mask:0xf bound_ctrl:1
	v_ashrrev_i32_e32 v67, 31, v66
	v_cndmask_b32_e32 v34, v43, v41, vcc
	v_cndmask_b32_e32 v36, v47, v39, vcc
	v_mov_b32_dpp v48, v35 row_ror:8 row_mask:0xf bank_mask:0xf bound_ctrl:1
	v_pk_mul_f32 v[30:31], v[30:31], v[30:31]
	v_pk_mul_f32 v[32:33], v[32:33], v[32:33]
	v_pk_mul_f32 v[28:29], v[28:29], v[28:29]
	v_cvt_pk_bf16_f32 v26, v26, v27
	v_pk_mul_f32 v[20:21], v[20:21], v[20:21]
	v_cvt_pk_bf16_f32 v22, v22, v23
	v_cvt_pk_bf16_f32 v23, v24, v25
	v_cvt_pk_bf16_f32 v24, v18, v19
	v_cvt_pk_bf16_f32 v14, v14, v15
	v_cvt_pk_bf16_f32 v15, v16, v17
	v_cvt_pk_bf16_f32 v11, v12, v13
	v_cvt_pk_bf16_f32 v9, v4, v5
	v_cndmask_b32_e32 v3, v10, v8, vcc
	v_mov_b32_dpp v60, v53 row_ror:8 row_mask:0xf bank_mask:0xf bound_ctrl:1
	v_mov_b32_dpp v61, v52 row_ror:8 row_mask:0xf bank_mask:0xf bound_ctrl:1
	v_cndmask_b32_e32 v53, v65, v59, vcc
	v_cndmask_b32_e32 v52, v64, v58, vcc
	v_lshlrev_b64 v[58:59], 13, v[66:67]
	v_cndmask_b32_e32 v37, v46, v38, vcc
	v_mov_b32_dpp v45, v36 row_ror:8 row_mask:0xf bank_mask:0xf bound_ctrl:1
	v_mov_b32_dpp v49, v34 row_ror:8 row_mask:0xf bank_mask:0xf bound_ctrl:1
	v_cndmask_b32_e32 v36, v48, v42, vcc
	v_add_u32_e32 v42, 0x90, v144
	v_cvt_pk_bf16_f32 v30, v30, v31
	v_cvt_pk_bf16_f32 v31, v32, v33
	v_cvt_pk_bf16_f32 v27, v28, v29
	v_cvt_pk_bf16_f32 v25, v20, v21
	v_cndmask_b32_e32 v19, v26, v24, vcc
	v_cndmask_b32_e32 v2, v11, v9, vcc
	v_cndmask_b32_e32 v4, v15, v7, vcc
	v_mov_b32_dpp v16, v3 row_ror:8 row_mask:0xf bank_mask:0xf bound_ctrl:1
	v_lshl_add_u64 v[58:59], s[18:19], 0, v[58:59]
	v_mov_b32_dpp v44, v37 row_ror:8 row_mask:0xf bank_mask:0xf bound_ctrl:1
	v_cndmask_b32_e32 v37, v49, v43, vcc
	v_ashrrev_i32_e32 v43, 31, v42
	v_cndmask_b32_e32 v18, v27, v25, vcc
	v_cndmask_b32_e32 v20, v31, v23, vcc
	v_mov_b32_dpp v32, v19 row_ror:8 row_mask:0xf bank_mask:0xf bound_ctrl:1
	v_cndmask_b32_e32 v5, v14, v6, vcc
	v_mov_b32_dpp v13, v4 row_ror:8 row_mask:0xf bank_mask:0xf bound_ctrl:1
	v_mov_b32_dpp v17, v2 row_ror:8 row_mask:0xf bank_mask:0xf bound_ctrl:1
	v_cndmask_b32_e32 v4, v16, v10, vcc
	v_add_u32_e32 v10, 0xb0, v144
	v_lshl_add_u64 v[58:59], v[58:59], 0, s[0:1]
	v_lshlrev_b64 v[42:43], 13, v[42:43]
	v_cndmask_b32_e32 v21, v30, v22, vcc
	v_mov_b32_dpp v29, v20 row_ror:8 row_mask:0xf bank_mask:0xf bound_ctrl:1
	v_mov_b32_dpp v33, v18 row_ror:8 row_mask:0xf bank_mask:0xf bound_ctrl:1
	v_cndmask_b32_e32 v20, v32, v26, vcc
	v_add_u32_e32 v26, 0xa0, v144
	v_mov_b32_dpp v12, v5 row_ror:8 row_mask:0xf bank_mask:0xf bound_ctrl:1
	v_cndmask_b32_e32 v5, v17, v11, vcc
	v_ashrrev_i32_e32 v11, 31, v10
	v_lshl_add_u64 v[58:59], v[58:59], 0, v[142:143]
	v_lshl_add_u64 v[42:43], s[18:19], 0, v[42:43]
	v_mov_b32_dpp v28, v21 row_ror:8 row_mask:0xf bank_mask:0xf bound_ctrl:1
	v_cndmask_b32_e32 v21, v33, v27, vcc
	v_ashrrev_i32_e32 v27, 31, v26
	v_lshlrev_b64 v[10:11], 13, v[10:11]
	v_cndmask_b32_e32 v51, v61, v63, vcc
	v_cndmask_b32_e32 v50, v60, v62, vcc
	v_lshl_add_u64 v[58:59], v[58:59], 0, v[114:115]
	v_lshl_add_u64 v[42:43], v[42:43], 0, s[0:1]
	v_lshlrev_b64 v[26:27], 13, v[26:27]
	v_lshl_add_u64 v[10:11], s[18:19], 0, v[10:11]
	global_store_dwordx4 v[58:59], v[50:53], off
	v_lshl_add_u64 v[42:43], v[42:43], 0, v[142:143]
	v_lshl_add_u64 v[26:27], s[18:19], 0, v[26:27]
	v_add_co_u32_e64 v50, s[4:5], s51, v58
	v_lshl_add_u64 v[10:11], v[10:11], 0, s[0:1]
	s_nop 0
	v_addc_co_u32_e64 v51, s[4:5], 0, v59, s[4:5]
	v_cndmask_b32_e32 v35, v45, v47, vcc
	v_cndmask_b32_e32 v34, v44, v46, vcc
	v_lshl_add_u64 v[42:43], v[42:43], 0, v[114:115]
	v_lshl_add_u64 v[26:27], v[26:27], 0, s[0:1]
	v_lshl_add_u64 v[10:11], v[10:11], 0, v[142:143]
	global_store_dwordx4 v[42:43], v[34:37], off
	v_lshl_add_u64 v[26:27], v[26:27], 0, v[142:143]
	v_cndmask_b32_e32 v3, v13, v15, vcc
	v_add_co_u32_e64 v34, s[4:5], s51, v42
	v_cndmask_b32_e32 v2, v12, v14, vcc
	v_lshl_add_u64 v[10:11], v[10:11], 0, v[114:115]
	v_cndmask_b32_e32 v105, v105, v113, vcc
	v_cndmask_b32_e32 v104, v104, v112, vcc
	v_cndmask_b32_e32 v103, v103, v109, vcc
	v_cndmask_b32_e32 v102, v102, v108, vcc
	v_cndmask_b32_e32 v89, v89, v97, vcc
	v_cndmask_b32_e32 v88, v88, v96, vcc
	v_cndmask_b32_e32 v87, v87, v93, vcc
	v_cndmask_b32_e32 v86, v86, v92, vcc
	v_cndmask_b32_e32 v57, v57, v65, vcc
	v_cndmask_b32_e32 v56, v56, v64, vcc
	v_cndmask_b32_e32 v55, v55, v61, vcc
	v_cndmask_b32_e32 v54, v54, v60, vcc
	v_cndmask_b32_e32 v41, v41, v49, vcc
	v_cndmask_b32_e32 v40, v40, v48, vcc
	v_cndmask_b32_e32 v39, v39, v45, vcc
	v_cndmask_b32_e32 v38, v38, v44, vcc
	v_addc_co_u32_e64 v35, s[4:5], 0, v43, s[4:5]
	v_cndmask_b32_e32 v19, v29, v31, vcc
	v_cndmask_b32_e32 v18, v28, v30, vcc
	v_cndmask_b32_e32 v25, v25, v33, vcc
	v_cndmask_b32_e32 v24, v24, v32, vcc
	v_cndmask_b32_e32 v23, v23, v29, vcc
	v_cndmask_b32_e32 v22, v22, v28, vcc
	v_lshl_add_u64 v[26:27], v[26:27], 0, v[114:115]
	v_cndmask_b32_e32 v9, v9, v17, vcc
	v_cndmask_b32_e32 v8, v8, v16, vcc
	v_cndmask_b32_e32 v7, v7, v13, vcc
	v_cndmask_b32_e32 v6, v6, v12, vcc
	global_store_dwordx4 v[10:11], v[2:5], off
	global_store_dwordx4 v[26:27], v[18:21], off
	s_mov_b64 s[0:1], -1
	v_add_co_u32_e32 v2, vcc, 0x10000, v10
	v_add_co_u32_e64 v18, s[4:5], s51, v26
	s_nop 0
	v_addc_co_u32_e32 v3, vcc, 0, v11, vcc
	v_addc_co_u32_e64 v19, s[4:5], 0, v27, s[4:5]
	s_andn2_b64 vcc, exec, s[2:3]
	global_store_dwordx4 v[116:117], v[120:123], off
	global_store_dwordx4 v[98:99], v[102:105], off
	global_store_dwordx4 v[82:83], v[86:89], off
	global_store_dwordx4 v[50:51], v[54:57], off
	global_store_dwordx4 v[34:35], v[38:41], off
	global_store_dwordx4 v[18:19], v[22:25], off
	global_store_dwordx4 v[2:3], v[6:9], off
	s_cbranch_vccnz .LBB0_960
	s_andn2_b64 vcc, exec, s[14:15]
	s_cbranch_vccnz .LBB0_959
	s_barrier
	s_branch .LBB0_959

	.amdhsa_kernel _Z3fwd4Args
		.amdhsa_group_segment_fixed_size 0
		.amdhsa_private_segment_fixed_size 0
		.amdhsa_kernarg_size 416
		.amdhsa_user_sgpr_count 2
		.amdhsa_user_sgpr_dispatch_ptr 0
		.amdhsa_user_sgpr_queue_ptr 0
		.amdhsa_user_sgpr_kernarg_segment_ptr 1
		.amdhsa_user_sgpr_dispatch_id 0
		.amdhsa_user_sgpr_kernarg_preload_length 0
		.amdhsa_user_sgpr_kernarg_preload_offset 0
		.amdhsa_user_sgpr_private_segment_size 0
		.amdhsa_uses_dynamic_stack 0
		.amdhsa_enable_private_segment 0
		.amdhsa_system_sgpr_workgroup_id_x 1
		.amdhsa_system_sgpr_workgroup_id_y 0
		.amdhsa_system_sgpr_workgroup_id_z 0
		.amdhsa_system_sgpr_workgroup_info 0
		.amdhsa_system_vgpr_workitem_id 0
		.amdhsa_next_free_vgpr 256
		.amdhsa_next_free_sgpr 99
		.amdhsa_accum_offset 256
		.amdhsa_reserve_vcc 1
		.amdhsa_float_round_mode_32 0
		.amdhsa_float_round_mode_16_64 0
		.amdhsa_float_denorm_mode_32 3
		.amdhsa_float_denorm_mode_16_64 3
		.amdhsa_dx10_clamp 1
		.amdhsa_ieee_mode 1
		.amdhsa_fp16_overflow 0
		.amdhsa_tg_split 0
		.amdhsa_exception_fp_ieee_invalid_op 0
		.amdhsa_exception_fp_denorm_src 0
		.amdhsa_exception_fp_ieee_div_zero 0
		.amdhsa_exception_fp_ieee_overflow 0
		.amdhsa_exception_fp_ieee_underflow 0
		.amdhsa_exception_fp_ieee_inexact 0
		.amdhsa_exception_int_div_zero 0
	.end_amdhsa_kernel

amdhsa.kernels:
  - .agpr_count:     0
    .args:
      - .offset:         0
        .size:           160
        .value_kind:     by_value
      - .offset:         160
        .size:           4
        .value_kind:     hidden_block_count_x
      - .offset:         164
        .size:           4
        .value_kind:     hidden_block_count_y
      - .offset:         168
        .size:           4
        .value_kind:     hidden_block_count_z
      - .offset:         172
        .size:           2
        .value_kind:     hidden_group_size_x
      - .offset:         174
        .size:           2
        .value_kind:     hidden_group_size_y
      - .offset:         176
        .size:           2
        .value_kind:     hidden_group_size_z
      - .offset:         178
        .size:           2
        .value_kind:     hidden_remainder_x
      - .offset:         180
        .size:           2
        .value_kind:     hidden_remainder_y
      - .offset:         182
        .size:           2
        .value_kind:     hidden_remainder_z
      - .offset:         200
        .size:           8
        .value_kind:     hidden_global_offset_x
      - .offset:         208
        .size:           8
        .value_kind:     hidden_global_offset_y
      - .offset:         216
        .size:           8
        .value_kind:     hidden_global_offset_z
      - .offset:         224
        .size:           2
        .value_kind:     hidden_grid_dims
      - .offset:         280
        .size:           4
        .value_kind:     hidden_dynamic_lds_size
    .group_segment_fixed_size: 0
    .kernarg_segment_align: 8
    .kernarg_segment_size: 416
    .language:       OpenCL C
    .language_version:
      - 2
      - 0
    .max_flat_workgroup_size: 512
    .name:           _Z3fwd4Args
    .private_segment_fixed_size: 0
    .sgpr_count:     105
    .sgpr_spill_count: 20
    .symbol:         _Z3fwd4Args.kd
    .uniform_work_group_size: 1
    .uses_dynamic_stack: false
    .vgpr_count:     256
    .vgpr_spill_count: 0
    .wavefront_size: 64
